# scan chunk loop: key-norm stage parameter quads fetched after the prefetch block, output-norm parameter quads fetched right after the stage barrier (both into dead v[240:251])
# speedup vs baseline: 1.0409x; 1.0012x over previous
; DI float sigmoidf_(float x) { return frcp(1.f + __expf(-x)); }
; DI f32x4 mfma16(bf16x8 a, bf16x8 b, f32x4 c) { return __builtin_amdgcn_mfma_f32_16x16x32_bf16(a, b, c, 0, 0, 0); }
; __device__ __forceinline__ void scan_item(const Params& p, int stream, int h, unsigned char* smem) {
;     ...
;     __syncthreads();
;     {
;       f32x4 dw = {0.f, 0.f, 0.f, 0.f}, da = dw, dg = dw;
; #pragma unroll
;       for (int ks = 0; ks < 2; ++ks) {
;         bf16x8 aw = *(const bf16x8*)(sTW + (ks << 10) + swz(r, q));
;         bf16x8 aa = *(const bf16x8*)(sAL + (ks << 10) + swz(r, q));
;         dw = mfma16(aw, bw[ks], dw);
;         da = mfma16(aa, ba[ks], da);
;       }
; #pragma unroll
;       for (int ks = 0; ks < 4; ++ks) {
;         bf16x8 ag = *(const bf16x8*)(sSG + (ks << 10) + swz(r, q));
;         dg = mfma16(ag, bg[ks], dg);
;       }
;       const int ch = wave * 16 + r;
; #pragma unroll
;       for (int jj = 0; jj < 4; ++jj) {
;         const int tk = q * 4 + jj;
;         float z = -(w0c + dw[jj]);
;         float sp = z > 20.f ? z : __logf(1.f + __expf(z));
;         float logw = -sp - 0.5f;
;         sW[tk * 64 + ch] = __expf(-__expf(logw));
;         sKKA[tk * 64 + ch] = sigmoidf_(a0c + da[jj]);
;         sG[tk * 64 + ch] = dg[jj];
;       }
;     }
;     __syncthreads();
;     {
;       float kkw[4], kaw[4], rkw[4];
;       {
;         const float4 a4 = *(const float4*)(p.in[19] + hc), b4 = *(const float4*)(p.in[20] + hc), c4v = *(const float4*)(p.in[21] + hc);
;         kkw[0] = a4.x; kkw[1] = a4.y; kkw[2] = a4.z; kkw[3] = a4.w;
;         kaw[0] = b4.x; kaw[1] = b4.y; kaw[2] = b4.z; kaw[3] = b4.w;
;         rkw[0] = c4v.x; rkw[1] = c4v.y; rkw[2] = c4v.z; rkw[3] = c4v.w;
;       }
.LBB0_1595:
	global_load_dwordx4 v[240:243], v[154:155], off
	global_load_dwordx4 v[244:247], v[156:157], off
	global_load_dwordx4 v[248:251], v[158:159], off
	s_waitcnt lgkmcnt(0)
	s_barrier
	ds_read_b128 v[68:71], v222 offset:37120
	ds_read_b128 v[72:75], v222 offset:38144
	ds_read_b128 v[76:79], v221 offset:33024
	ds_read_b128 v[80:83], v221 offset:34048
	s_waitcnt lgkmcnt(1)
	v_mfma_f32_16x16x32_bf16 v[76:79], v[76:79], v[4:7], 0
	s_waitcnt lgkmcnt(0)
	v_mfma_f32_16x16x32_bf16 v[76:79], v[80:83], v[8:11], v[76:79]
	ds_read_b128 v[80:83], v221 offset:36096
	v_mfma_f32_16x16x32_bf16 v[68:71], v[68:71], v[20:23], 0
	v_mfma_f32_16x16x32_bf16 v[68:71], v[72:75], v[24:27], v[68:71]
	s_nop 4
	v_add_f32_e32 v0, v93, v76
	v_mul_f32_e32 v1, 0xbfb8aa3b, v0
	v_exp_f32_e32 v1, v1
	ds_read_b128 v[72:75], v221 offset:35072
	s_waitcnt lgkmcnt(0)
	v_mfma_f32_16x16x32_bf16 v[72:75], v[72:75], v[12:15], 0
	v_add_f32_e32 v1, 1.0, v1
	v_cmp_gt_f32_e32 vcc, s63, v1
	ds_read_b128 v[84:87], v222 offset:39168
	ds_read_b128 v[88:91], v222 offset:40192
	v_cndmask_b32_e64 v3, 0, 32, vcc
	v_ldexp_f32 v1, v1, v3
	v_log_f32_e32 v1, v1
	v_add_f32_e32 v3, v93, v77
	v_cndmask_b32_e32 v76, 0, v193, vcc
	v_mfma_f32_16x16x32_bf16 v[72:75], v[80:83], v[16:19], v[72:75]
	v_mul_f32_e32 v77, 0x3f317217, v1
	v_fma_f32 v77, v1, s64, -v77
	v_fmac_f32_e32 v77, 0x3377d1cf, v1
	v_fmac_f32_e32 v77, 0x3f317217, v1
	v_cmp_lt_f32_e64 vcc, |v1|, s65
	s_nop 2
	v_add_f32_e32 v72, v97, v72
	v_mul_f32_e32 v72, 0xbfb8aa3b, v72
	v_cndmask_b32_e32 v1, v1, v77, vcc
	v_sub_f32_e32 v1, v1, v76
	v_cmp_gt_f32_e32 vcc, s62, v0
	v_exp_f32_e32 v72, v72
	v_add_f32_e32 v73, v97, v73
	v_cndmask_b32_e64 v0, v1, -v0, vcc
	v_mul_f32_e32 v1, 0xbfb8aa3b, v3
	v_exp_f32_e32 v1, v1
	v_sub_f32_e32 v0, -0.5, v0
	v_mul_f32_e32 v0, 0x3fb8aa3b, v0
	v_exp_f32_e32 v0, v0
	v_add_f32_e32 v1, 1.0, v1
	v_cmp_gt_f32_e32 vcc, s63, v1
	v_mul_f32_e32 v73, 0xbfb8aa3b, v73
	v_mul_f32_e32 v0, 0xbfb8aa3b, v0
	v_cndmask_b32_e64 v76, 0, 32, vcc
	v_ldexp_f32 v1, v1, v76
	v_log_f32_e32 v1, v1
	v_exp_f32_e32 v0, v0
	v_exp_f32_e32 v73, v73
	v_add_f32_e32 v74, v97, v74
	v_mul_f32_e32 v76, 0x3f317217, v1
	v_fma_f32 v76, v1, s64, -v76
	v_fmac_f32_e32 v76, 0x3377d1cf, v1
	v_fmac_f32_e32 v76, 0x3f317217, v1
	v_cmp_lt_f32_e64 s[0:1], |v1|, s65
	s_waitcnt lgkmcnt(1)
	v_mfma_f32_16x16x32_bf16 v[68:71], v[84:87], v[28:31], v[68:71]
	v_mul_f32_e32 v74, 0xbfb8aa3b, v74
	v_cndmask_b32_e64 v1, v1, v76, s[0:1]
	v_cndmask_b32_e32 v76, 0, v193, vcc
	v_sub_f32_e32 v1, v1, v76
	v_cmp_gt_f32_e32 vcc, s62, v3
	v_exp_f32_e32 v74, v74
	s_waitcnt lgkmcnt(0)
	v_mfma_f32_16x16x32_bf16 v[68:71], v[88:91], v[32:35], v[68:71]
	v_cndmask_b32_e64 v1, v1, -v3, vcc
	v_add_f32_e32 v3, 1.0, v72
	v_add_f32_e32 v72, v93, v78
	v_mul_f32_e32 v76, 0xbfb8aa3b, v72
	v_exp_f32_e32 v76, v76
	v_sub_f32_e32 v1, -0.5, v1
	v_mul_f32_e32 v1, 0x3fb8aa3b, v1
	v_exp_f32_e32 v1, v1
	v_add_f32_e32 v76, 1.0, v76
	v_cmp_gt_f32_e32 vcc, s63, v76
	v_rcp_f32_e32 v3, v3
	v_mul_f32_e32 v1, 0xbfb8aa3b, v1
	v_cndmask_b32_e64 v77, 0, 32, vcc
	v_ldexp_f32 v76, v76, v77
	v_exp_f32_e32 v1, v1
	v_log_f32_e32 v76, v76
	v_add_f32_e32 v74, 1.0, v74
	v_rcp_f32_e32 v74, v74
	ds_write2st64_b32 v205, v0, v1 offset1:1
	v_mul_f32_e32 v1, 0x3f317217, v76
	v_fma_f32 v1, v76, s64, -v1
	v_fmac_f32_e32 v1, 0x3377d1cf, v76
	v_fmac_f32_e32 v1, 0x3f317217, v76
	v_cmp_lt_f32_e64 s[0:1], |v76|, s65
	v_add_f32_e32 v0, 1.0, v73
	v_cndmask_b32_e32 v73, 0, v193, vcc
	v_cndmask_b32_e64 v1, v76, v1, s[0:1]
	v_sub_f32_e32 v1, v1, v73
	v_cmp_gt_f32_e32 vcc, s62, v72
	v_rcp_f32_e32 v0, v0
	s_nop 0
	v_cndmask_b32_e64 v1, v1, -v72, vcc
	v_add_f32_e32 v72, v93, v79
	v_mul_f32_e32 v73, 0xbfb8aa3b, v72
	v_exp_f32_e32 v73, v73
	v_sub_f32_e32 v1, -0.5, v1
	v_mul_f32_e32 v1, 0x3fb8aa3b, v1
	v_exp_f32_e32 v1, v1
	v_add_f32_e32 v73, 1.0, v73
	v_cmp_gt_f32_e32 vcc, s63, v73
	v_mul_f32_e32 v1, 0xbfb8aa3b, v1
	s_nop 0
	v_cndmask_b32_e64 v76, 0, 32, vcc
	v_ldexp_f32 v73, v73, v76
	v_log_f32_e32 v73, v73
	v_exp_f32_e32 v1, v1
	v_mul_f32_e32 v76, 0x3f317217, v73
	v_fma_f32 v76, v73, s64, -v76
	v_fmac_f32_e32 v76, 0x3377d1cf, v73
	v_fmac_f32_e32 v76, 0x3f317217, v73
	v_cmp_lt_f32_e64 s[0:1], |v73|, s65
	s_nop 1
	v_cndmask_b32_e64 v73, v73, v76, s[0:1]
	v_cndmask_b32_e32 v76, 0, v193, vcc
	v_sub_f32_e32 v73, v73, v76
	v_cmp_gt_f32_e32 vcc, s62, v72
	s_nop 1
	v_cndmask_b32_e64 v72, v73, -v72, vcc
	v_sub_f32_e32 v72, -0.5, v72
	v_mul_f32_e32 v72, 0x3fb8aa3b, v72
	v_add_f32_e32 v73, v97, v75
	v_exp_f32_e32 v72, v72
	v_mul_f32_e32 v73, 0xbfb8aa3b, v73
	v_exp_f32_e32 v73, v73
	v_mul_f32_e32 v72, 0xbfb8aa3b, v72
	v_exp_f32_e32 v72, v72
	v_add_f32_e32 v73, 1.0, v73
	v_rcp_f32_e32 v73, v73
	ds_write2st64_b32 v205, v3, v0 offset0:48 offset1:49
	ds_write2st64_b32 v205, v68, v69 offset0:96 offset1:97
	ds_write2st64_b32 v205, v1, v72 offset0:2 offset1:3
	ds_write2st64_b32 v205, v74, v73 offset0:50 offset1:51
	ds_write2st64_b32 v205, v70, v71 offset0:98 offset1:99
	s_waitcnt lgkmcnt(0)
	s_barrier


; __device__ __forceinline__ void scan_item(const Params& p, int stream, int h, unsigned char* smem) {
;     ...
;       float4 k4 = *(const float4*)(sKp + et * 64 + ec);
;       float4 a4 = *(const float4*)(sKKA + et * 64 + ec);
;       float4 r4 = *(const float4*)(sR + et * 64 + ec);
;       float kr[4] = {k4.x, k4.y, k4.z, k4.w}, aa[4] = {a4.x, a4.y, a4.z, a4.w}, rr[4] = {r4.x, r4.y, r4.z, r4.w};
;       float kk[4], ss = 0.f;
; #pragma unroll
;       for (int j = 0; j < 4; ++j) { kk[j] = kr[j] * kkw[j]; ss += kk[j] * kk[j]; }
;       ss = row16_sum(ss);
;       const float inv = fminf(__builtin_amdgcn_rsqf(ss), 1e12f);
;       float kp[4], nk[4], ka[4], rk = 0.f;
; #pragma unroll
;       for (int j = 0; j < 4; ++j) {
;         kk[j] *= inv;
;         kp[j] = kr[j] * (1.f + (aa[j] - 1.f) * kaw[j]);
;         nk[j] = -kk[j]; ka[j] = kk[j] * aa[j];
;         rk += rr[j] * kp[j] * rkw[j];
;       }
;       rk = row16_sum(rk);
;       *(float4*)(sKp + et * 64 + ec) = make_float4(kp[0], kp[1], kp[2], kp[3]);
;       *(float4*)(sNKK + et * 64 + ec) = make_float4(nk[0], nk[1], nk[2], nk[3]);
;       *(float4*)(sKKA + et * 64 + ec) = make_float4(ka[0], ka[1], ka[2], ka[3]);
;       if ((tid & 15) == 0) sRK[et] = rk;
;     }
;     __syncthreads();
;     {
;       const int k = tid & 63, tq = tid >> 6;
;       float gam = 1.f;
;       {
;         float wv[12];
; #pragma unroll
;         for (int t = 0; t < 12; ++t) wv[t] = sW[t * 64 + k];
; #pragma unroll
;         for (int t = 0; t < 12; ++t) gam *= (t < 4 * tq) ? wv[t] : 1.f;
	ds_read_b128 v[80:83], v197 offset:4096
	ds_read_b128 v[84:87], v197 offset:12288
	ds_read_b128 v[88:91], v197 offset:16384
	s_waitcnt vmcnt(2) lgkmcnt(2)
	v_pk_mul_f32 v[0:1], v[240:241], v[80:81]
	s_waitcnt lgkmcnt(1)
	v_pk_add_f32 v[68:69], v[84:85], -1.0 op_sel_hi:[1,0]
	v_pk_mul_f32 v[232:233], v[0:1], v[0:1]
	s_waitcnt vmcnt(1)
	v_pk_fma_f32 v[68:69], v[244:245], v[68:69], 1.0 op_sel_hi:[1,1,0]
	s_nop 0
	v_pk_mul_f32 v[68:69], v[80:81], v[68:69]
	s_waitcnt lgkmcnt(0)
	v_mul_f32_e32 v3, v68, v88
	s_waitcnt vmcnt(0)
	v_fma_f32 v3, v248, v3, 0
	v_mul_f32_e32 v72, v69, v89
	v_fmac_f32_e32 v3, v249, v72
	v_pk_mul_f32 v[72:73], v[242:243], v[82:83]
	v_pk_add_f32 v[70:71], v[86:87], -1.0 op_sel_hi:[1,0]
	v_pk_mul_f32 v[76:77], v[72:73], v[72:73]
	v_pk_fma_f32 v[70:71], v[246:247], v[70:71], 1.0 op_sel_hi:[1,1,0]
	v_add_f32_e32 v74, v232, v233
	v_add_f32_e32 v74, v74, v76
	v_add_f32_e32 v74, v74, v77
	v_pk_mul_f32 v[70:71], v[82:83], v[70:71]
	ds_write_b128 v197, v[68:71] offset:4096
	v_add_f32_dpp v74, v74, v74 quad_perm:[1,0,3,2] row_mask:0xf bank_mask:0xf bound_ctrl:1
	v_mul_f32_e32 v76, v70, v90
	v_mul_f32_e32 v77, v71, v91
	v_add_f32_dpp v74, v74, v74 quad_perm:[2,3,0,1] row_mask:0xf bank_mask:0xf bound_ctrl:1
	v_fmac_f32_e32 v3, v250, v76
	v_fmac_f32_e32 v3, v251, v77
	v_add_f32_dpp v74, v74, v74 row_half_mirror row_mask:0xf bank_mask:0xf bound_ctrl:1
	s_nop 1
	v_add_f32_dpp v74, v74, v74 row_mirror row_mask:0xf bank_mask:0xf bound_ctrl:1
	v_rsq_f32_e32 v74, v74
	s_nop 0
	v_min_f32_e32 v70, 0x5368d4a5, v74
	v_pk_mul_f32 v[74:75], v[0:1], v[70:71] op_sel_hi:[1,0]
	v_add_f32_dpp v0, v3, v3 quad_perm:[1,0,3,2] row_mask:0xf bank_mask:0xf bound_ctrl:1
	v_pk_mul_f32 v[72:73], v[72:73], v[70:71] op_sel_hi:[1,0]
	v_xor_b32_e32 v69, 0x80000000, v75
	v_add_f32_dpp v0, v0, v0 quad_perm:[2,3,0,1] row_mask:0xf bank_mask:0xf bound_ctrl:1
	v_xor_b32_e32 v68, 0x80000000, v74
	v_xor_b32_e32 v71, 0x80000000, v73
	v_xor_b32_e32 v70, 0x80000000, v72
	v_add_f32_dpp v0, v0, v0 row_half_mirror row_mask:0xf bank_mask:0xf bound_ctrl:1
	v_mov_b32_e32 v1, v2
	ds_write_b128 v197, v[68:71] offset:8192
	v_pk_mul_f32 v[68:69], v[84:85], v[74:75]
	v_mov_b32_dpp v1, v0 row_mirror row_mask:0xf bank_mask:0xf
	v_pk_mul_f32 v[70:71], v[86:87], v[72:73]
	ds_write_b128 v197, v[68:71] offset:12288
	s_and_saveexec_b64 s[0:1], s[20:21]
	v_add_f32_e32 v0, v0, v1
	ds_write_b32 v99, v0 offset:32768
	s_or_b64 exec, exec, s[0:1]
	s_waitcnt lgkmcnt(0)
	s_barrier
	ds_read2st64_b32 v[72:73], v199 offset0:4 offset1:5
	ds_read2st64_b32 v[70:71], v199 offset0:6 offset1:7
	ds_read2st64_b32 v[68:69], v199 offset0:8 offset1:9
	ds_read2st64_b32 v[0:1], v199 offset0:10 offset1:11
	v_mov_b32_e32 v3, 1.0
	s_and_saveexec_b64 s[0:1], s[58:59]
	s_cbranch_execz .LBB0_1599
	ds_read2st64_b32 v[74:75], v199 offset1:1
	ds_read2st64_b32 v[76:77], v199 offset0:2 offset1:3
	s_waitcnt lgkmcnt(1)
	v_mul_f32_e32 v3, v75, v74
	s_waitcnt lgkmcnt(0)
	v_mul_f32_e32 v3, v76, v3
	v_mul_f32_e32 v3, v77, v3

; __device__ __forceinline__ void scan_item(const Params& p, int stream, int h, unsigned char* smem) {
;     ...
;     __syncthreads();
;     {
;       float lnw[4], lnb[4];
;       {
;         const float4 a4 = *(const float4*)(p.in[22] + hc), b4 = *(const float4*)(p.in[23] + hc);
;         lnw[0] = a4.x; lnw[1] = a4.y; lnw[2] = a4.z; lnw[3] = a4.w;
;         lnb[0] = b4.x; lnb[1] = b4.y; lnb[2] = b4.z; lnb[3] = b4.w;
;       }
;       float4 y4 = *(const float4*)(sY + et * 64 + ec);
;       float yy[4] = {y4.x, y4.y, y4.z, y4.w};
;       float s1 = row16_sum(yy[0] + yy[1] + yy[2] + yy[3]);
;       const float mean = s1 * (1.f / 64.f);
;       float s2 = 0.f;
; #pragma unroll
;       for (int j = 0; j < 4; ++j) { yy[j] -= mean; s2 += yy[j] * yy[j]; }
;       s2 = row16_sum(s2);
;       const float rs = __builtin_amdgcn_rsqf(s2 * (1.f / 64.f) + 64e-5f);
.LBB0_1608:
	s_or_b64 exec, exec, s[0:1]
	s_barrier
	ds_read_b128 v[68:71], v204 offset:28672
	v_cmp_gt_i32_e32 vcc, s40, v170
	s_and_saveexec_b64 s[0:1], vcc
	global_load_dwordx4 v[240:243], v[160:161], off
	global_load_dwordx4 v[244:247], v[162:163], off
	s_mov_b64 exec, s[0:1]
	s_waitcnt lgkmcnt(0)
	v_add_f32_e32 v0, v68, v69
	v_add_f32_e32 v0, v0, v70
	v_add_f32_e32 v0, v0, v71
	s_nop 1
	v_add_f32_dpp v0, v0, v0 quad_perm:[1,0,3,2] row_mask:0xf bank_mask:0xf bound_ctrl:1
	s_nop 1
	v_add_f32_dpp v0, v0, v0 quad_perm:[2,3,0,1] row_mask:0xf bank_mask:0xf bound_ctrl:1
	s_nop 1
	v_add_f32_dpp v0, v0, v0 row_half_mirror row_mask:0xf bank_mask:0xf bound_ctrl:1
	s_nop 1
	v_add_f32_dpp v0, v0, v0 row_mirror row_mask:0xf bank_mask:0xf bound_ctrl:1
	v_mul_f32_e32 v72, 0x3c800000, v0
	v_pk_add_f32 v[0:1], v[68:69], v[72:73] op_sel_hi:[1,0] neg_lo:[0,1] neg_hi:[0,1]
	v_pk_add_f32 v[68:69], v[70:71], v[72:73] op_sel_hi:[1,0] neg_lo:[0,1] neg_hi:[0,1]
	v_pk_mul_f32 v[70:71], v[0:1], v[0:1]
	v_pk_mul_f32 v[72:73], v[68:69], v[68:69]
	v_add_f32_e32 v3, v70, v71
	v_add_f32_e32 v3, v72, v3
	v_add_f32_e32 v3, v73, v3
	v_mov_b32_e32 v70, v2
	s_nop 0
	v_add_f32_dpp v3, v3, v3 quad_perm:[1,0,3,2] row_mask:0xf bank_mask:0xf bound_ctrl:1
	s_nop 1
	v_add_f32_dpp v3, v3, v3 quad_perm:[2,3,0,1] row_mask:0xf bank_mask:0xf bound_ctrl:1
	s_nop 1
	v_add_f32_dpp v3, v3, v3 row_half_mirror row_mask:0xf bank_mask:0xf bound_ctrl:1
	s_nop 1
	v_mov_b32_dpp v70, v3 row_mirror row_mask:0xf bank_mask:0xf
	s_and_saveexec_b64 s[0:1], vcc
	s_cbranch_execz .LBB0_1610
	v_add_f32_e32 v3, v3, v70
	ds_read_b32 v86, v99 offset:32768
	ds_read_b128 v[70:73], v204 offset:24576


; __device__ __forceinline__ void scan_item(const Params& p, int stream, int h, unsigned char* smem) {
;     ...
;       const float rs = __builtin_amdgcn_rsqf(s2 * (1.f / 64.f) + 64e-5f);
;       const float rk = sRK[et];
;       float4 v4 = *(const float4*)(sV + et * 64 + ec);
;       float4 g4 = *(const float4*)(sG + et * 64 + ec);
;       const float vv[4] = {v4.x, v4.y, v4.z, v4.w}, gg[4] = {g4.x, g4.y, g4.z, g4.w};
;       float o[4];
; #pragma unroll
;       for (int j = 0; j < 4; ++j) o[j] = (yy[j] * rs * lnw[j] + lnb[j] + rk * vv[j]) * gg[j];
;       u32x2 ov = {pack2(o[0], o[1]), pack2(o[2], o[3])};
;       if (t0 < T) *(u32x2*)(MIX + (size_t)(row0 + t0 + et) * 1024 + hc) = ov;
	v_fmamk_f32 v3, v3, 0x3c800000, v173
	v_rsq_f32_e32 v84, v3
	v_ashrrev_i32_e32 v171, 31, v170
	v_pk_mul_f32 v[68:69], v[68:69], v[84:85] op_sel_hi:[1,0]
	v_pk_mul_f32 v[0:1], v[0:1], v[84:85] op_sel_hi:[1,0]
	s_waitcnt vmcnt(0)
	v_pk_fma_f32 v[68:69], v[68:69], v[242:243], v[246:247]
	ds_read_b128 v[80:83], v197 offset:20480
	v_pk_fma_f32 v[0:1], v[0:1], v[240:241], v[244:245]
	s_waitcnt lgkmcnt(0)
	v_pk_fma_f32 v[68:69], v[86:87], v[82:83], v[68:69] op_sel_hi:[0,1,1]
	v_pk_fma_f32 v[0:1], v[86:87], v[80:81], v[0:1] op_sel_hi:[0,1,1]
	v_pk_mul_f32 v[68:69], v[72:73], v[68:69]
	v_pk_mul_f32 v[0:1], v[70:71], v[0:1]
	v_cvt_pk_bf16_f32 v69, v68, v69
	v_cvt_pk_bf16_f32 v68, v0, v1
	v_lshl_add_u64 v[0:1], v[124:125], 0, v[170:171]
	v_lshlrev_b64 v[0:1], 11, v[0:1]
	v_lshl_add_u64 v[0:1], v[118:119], 0, v[0:1]
	global_store_dwordx2 v[0:1], v[68:69], off
